# GEMM tile loops: next-tile idx/8 and idx%8 by shift and mask instead of the float-reciprocal integer division (group height is always 8)
# speedup vs baseline: 1.0046x; 1.0046x over previous
;     __host__ __device__ bool next(int i, Unit& u) const {
;         const long L = (long)i * G + c; if (L >= nwg) return false;
;         int wgid = (int)L; { const int q = nwg / NXCD, r = nwg % NXCD, xcd = wgid % NXCD, off = wgid / NXCD; wgid = (xcd < r ? xcd * (q + 1) : r * (q + 1) + (xcd - r) * q) + off; }
;         const int nig = WGM * nN, gid = wgid / nig, fm = gid * WGM, gsz = (nM - fm) < WGM ? (nM - fm) : WGM;
;         u.pm = fm + ((wgid % nig) % gsz); u.pn = (wgid % nig) / gsz; return true;
;     }
; template <class Epi, class Sched, bool ALIGN_EPI = false, bool SP2 = false>
; __device__ __forceinline__ void gemm_phase(PG8_LAS unsigned char* lds, const Gemm g, const Sched& S, const Epi& E, const int tid_) {
;     ...
;         const bool has_next = S.next(ui + 1, nxt);
;         const char* nA = has_next ? (const char*)g.A + (size_t)nxt.pm * tstep : cA; const char* nB = has_next ? (const char*)g.Bt + (size_t)nxt.pn * tstep : cB;
.LBB0_21:
	s_add_i32 s53, s53, 1
	s_mul_i32 s2, s53, s52
	s_mul_hi_u32 s3, s53, s90
	s_add_i32 s3, s3, s2
	s_mul_i32 s2, s53, s90
	s_add_u32 s2, s2, s91
	s_addc_u32 s3, s3, s34
	v_mov_b64_e32 v[4:5], 0x1600
	v_cmp_lt_i64_e64 s[6:7], s[2:3], v[4:5]
	v_mov_b64_e32 v[4:5], 0x15ff
	v_cmp_gt_i64_e32 vcc, s[2:3], v[4:5]
	s_cbranch_vccnz .LBB0_23
	s_ashr_i32 s3, s2, 31
	s_lshr_b32 s3, s3, 29
	s_add_i32 s3, s2, s3
	s_ashr_i32 s14, s3, 3
	s_and_b32 s3, s3, -8
	s_sub_i32 s2, s2, s3
	s_cmp_lt_i32 s2, 0
	s_cselect_b32 s3, s71, 0x2c0
	s_mul_i32 s2, s2, s3
	s_add_i32 s2, s2, s14
	s_mul_hi_i32 s3, s2, 0x2e8ba2e9
	s_lshr_b32 s14, s3, 31
	s_ashr_i32 s3, s3, 5
	s_add_i32 s3, s3, s14
	s_lshl_b32 s15, s3, 3
	s_sub_i32 s14, 0x100, s15
	s_min_i32 s16, s14, 8
	s_mulk_i32 s3, 0xb0
	s_sub_i32 s2, s2, s3
	s_lshr_b32 s14, s2, 3
	s_and_b32 s2, s2, 7
	s_add_i32 s16, s15, s2

;     __host__ __device__ bool next(int i, Unit& u) const {
;         const long L = (long)i * G + c; if (L >= nwg) return false;
;         int wgid = (int)L; { const int q = nwg / NXCD, r = nwg % NXCD, xcd = wgid % NXCD, off = wgid / NXCD; wgid = (xcd < r ? xcd * (q + 1) : r * (q + 1) + (xcd - r) * q) + off; }
;         const int nig = WGM * nN, gid = wgid / nig, fm = gid * WGM, gsz = (nM - fm) < WGM ? (nM - fm) : WGM;
;         u.pm = fm + ((wgid % nig) % gsz); u.pn = (wgid % nig) / gsz; return true;
;     }
.LBB0_362:
	s_add_i32 s86, s86, 1
	s_mul_i32 s2, s86, s83
	s_mul_hi_u32 s3, s86, s90
	s_add_i32 s3, s3, s2
	s_mul_i32 s2, s86, s90
	s_add_u32 s2, s2, s91
	s_addc_u32 s3, s3, s1
	v_mov_b64_e32 v[4:5], s[92:93]
	v_cmp_ge_i64_e32 vcc, s[2:3], v[4:5]
	v_cmp_lt_i64_e64 s[8:9], s[2:3], v[4:5]
	s_cbranch_vccnz .LBB0_364
	s_ashr_i32 s3, s2, 31
	s_lshr_b32 s3, s3, 29
	s_add_i32 s3, s2, s3
	s_ashr_i32 s6, s3, 3
	s_and_b32 s3, s3, -8
	s_sub_i32 s2, s2, s3
	s_lshr_b32 s3, s2, 31
	s_or_b32 s3, s29, s3
	s_mul_i32 s2, s3, s2
	s_add_i32 s2, s2, s6
	s_abs_i32 s6, s2
	s_mul_hi_u32 s7, s6, s87
	s_mul_i32 s10, s7, s60
	s_sub_i32 s6, s6, s10
	s_ashr_i32 s3, s2, 31
	s_add_i32 s10, s7, 1
	s_sub_i32 s11, s6, s60
	s_cmp_ge_u32 s6, s60
	s_cselect_b32 s7, s10, s7
	s_cselect_b32 s6, s11, s6
	s_add_i32 s10, s7, 1
	s_cmp_ge_u32 s6, s60
	s_cselect_b32 s6, s10, s7
	s_xor_b32 s6, s6, s3
	s_sub_i32 s3, s6, s3
	s_lshl_b32 s6, s3, 3
	s_sub_i32 s7, 0x100, s6
	s_min_i32 s7, s7, 8
	s_mul_i32 s3, s3, s60
	s_sub_i32 s2, s2, s3
	s_lshr_b32 s40, s2, 3
	s_and_b32 s2, s2, 7
	s_add_i32 s41, s2, s6

;     __host__ __device__ bool next(int i, Unit& u) const {
;         const long L = (long)i * G + c; if (L >= nwg) return false;
;         int wgid = (int)L; { const int q = nwg / NXCD, r = nwg % NXCD, xcd = wgid % NXCD, off = wgid / NXCD; wgid = (xcd < r ? xcd * (q + 1) : r * (q + 1) + (xcd - r) * q) + off; }
;         const int nig = WGM * nN, gid = wgid / nig, fm = gid * WGM, gsz = (nM - fm) < WGM ? (nM - fm) : WGM;
;         u.pm = fm + ((wgid % nig) % gsz); u.pn = (wgid % nig) / gsz; return true;
;     }
.LBB0_522:
	s_ashr_i32 s2, s14, 3
	s_add_i32 s2, s25, s2
	s_ashr_i32 s3, s2, 31
	s_lshr_b32 s3, s3, 27
	s_add_i32 s3, s2, s3
	s_ashr_i32 s14, s3, 5
	s_lshl_b32 s14, s14, 3
	s_sub_i32 s15, 0x100, s14
	s_min_i32 s15, s15, 8
	s_andn2_b32 s3, s3, 31
	s_sub_i32 s2, s2, s3
	s_lshr_b32 s25, s2, 3
	s_and_b32 s2, s2, 7
	s_add_i32 s77, s14, s2
